# x->bf16 conversion inside the first projection phase: 4 rows per trip (second row pair's loads issued before the first pair's reduction)
# baseline (speedup 1.0000x reference)
.LBB0_111:
	v_lshl_add_u64 v[28:29], s[6:7], 0, v[148:149]
	v_lshl_add_u64 v[36:37], s[8:9], 0, v[148:149]
	global_load_dwordx4 v[8:11], v[28:29], off
	global_load_dwordx4 v[12:15], v[28:29], off offset:1024
	global_load_dwordx4 v[16:19], v[36:37], off
	global_load_dwordx4 v[20:23], v[36:37], off offset:1024
	global_load_dwordx4 v[24:27], v[28:29], off offset:2048
	s_nop 0
	global_load_dwordx4 v[28:31], v[28:29], off offset:3072
	s_nop 0
	global_load_dwordx4 v[32:35], v[36:37], off offset:2048
	s_nop 0
	global_load_dwordx4 v[36:39], v[36:37], off offset:3072
	s_add_i32 s3, s3, 16
	v_lshl_add_u64 v[42:43], s[4:5], 0, v[146:147]
	s_add_u32 s4, s4, 0x8000
	s_addc_u32 s5, s5, 0
	s_add_u32 s6, s6, 0x10000
	s_addc_u32 s7, s7, 0
	s_add_u32 s8, s8, 0x10000
	s_addc_u32 s9, s9, 0
	v_lshl_add_u64 v[40:41], s[10:11], 0, v[146:147]
	s_add_u32 s10, s10, 0x8000
	s_addc_u32 s11, s11, 0
	s_cmp_lt_i32 s3, s2
	v_lshl_add_u64 v[96:97], s[6:7], 0, v[148:149]
	v_lshl_add_u64 v[104:105], s[8:9], 0, v[148:149]
	global_load_dwordx4 v[76:79], v[96:97], off
	global_load_dwordx4 v[80:83], v[96:97], off offset:1024
	global_load_dwordx4 v[84:87], v[104:105], off
	global_load_dwordx4 v[88:91], v[104:105], off offset:1024
	global_load_dwordx4 v[92:95], v[96:97], off offset:2048
	s_nop 0
	global_load_dwordx4 v[96:99], v[96:97], off offset:3072
	s_nop 0
	global_load_dwordx4 v[100:103], v[104:105], off offset:2048
	s_nop 0
	global_load_dwordx4 v[104:107], v[104:105], off offset:3072
	s_add_i32 s3, s3, 16
	v_lshl_add_u64 v[110:111], s[4:5], 0, v[146:147]
	s_add_u32 s4, s4, 0x8000
	s_addc_u32 s5, s5, 0
	s_add_u32 s6, s6, 0x10000
	s_addc_u32 s7, s7, 0
	s_add_u32 s8, s8, 0x10000
	s_addc_u32 s9, s9, 0
	v_lshl_add_u64 v[108:109], s[10:11], 0, v[146:147]
	s_add_u32 s10, s10, 0x8000
	s_addc_u32 s11, s11, 0
	s_cmp_lt_i32 s3, s2
	s_waitcnt vmcnt(15)
	v_mov_b32_e32 v46, v9
	s_waitcnt vmcnt(14)
	v_mov_b32_e32 v47, v13
	s_waitcnt vmcnt(13)
	v_mov_b32_e32 v54, v17
	s_waitcnt vmcnt(12)
	v_mov_b32_e32 v55, v21
	v_mov_b32_e32 v44, v8
	v_mov_b32_e32 v45, v12
	v_mov_b32_e32 v52, v16
	v_mov_b32_e32 v53, v20
	s_waitcnt vmcnt(11)
	v_mov_b32_e32 v62, v25
	s_waitcnt vmcnt(10)
	v_mov_b32_e32 v63, v29
	s_waitcnt vmcnt(9)
	v_mov_b32_e32 v68, v33
	s_waitcnt vmcnt(8)
	v_mov_b32_e32 v69, v37
	v_pk_mul_f32 v[46:47], v[46:47], v[46:47]
	v_pk_mul_f32 v[54:55], v[54:55], v[54:55]
	v_mov_b32_e32 v48, v10
	v_mov_b32_e32 v49, v14
	v_mov_b32_e32 v56, v18
	v_mov_b32_e32 v57, v22
	v_mov_b32_e32 v60, v24
	v_mov_b32_e32 v61, v28
	v_mov_b32_e32 v66, v32
	v_mov_b32_e32 v67, v36
	v_pk_mul_f32 v[62:63], v[62:63], v[62:63]
	v_pk_mul_f32 v[68:69], v[68:69], v[68:69]
	v_pk_fma_f32 v[44:45], v[44:45], v[44:45], v[46:47]
	v_pk_fma_f32 v[46:47], v[52:53], v[52:53], v[54:55]
	v_mov_b32_e32 v50, v11
	v_mov_b32_e32 v51, v15
	v_mov_b32_e32 v58, v19
	v_mov_b32_e32 v59, v23
	v_mov_b32_e32 v64, v26
	v_mov_b32_e32 v65, v30
	v_mov_b32_e32 v72, v34
	v_mov_b32_e32 v73, v38
	v_pk_fma_f32 v[52:53], v[60:61], v[60:61], v[62:63]
	v_pk_fma_f32 v[54:55], v[66:67], v[66:67], v[68:69]
	v_pk_fma_f32 v[44:45], v[48:49], v[48:49], v[44:45]
	v_pk_fma_f32 v[46:47], v[56:57], v[56:57], v[46:47]
	v_mov_b32_e32 v70, v27
	v_mov_b32_e32 v71, v31
	v_mov_b32_e32 v74, v35
	v_mov_b32_e32 v75, v39
	v_pk_fma_f32 v[48:49], v[64:65], v[64:65], v[52:53]
	v_pk_fma_f32 v[52:53], v[72:73], v[72:73], v[54:55]
	v_pk_fma_f32 v[44:45], v[50:51], v[50:51], v[44:45]
	v_pk_fma_f32 v[46:47], v[58:59], v[58:59], v[46:47]
	v_pk_fma_f32 v[48:49], v[70:71], v[70:71], v[48:49]
	v_pk_fma_f32 v[50:51], v[74:75], v[74:75], v[52:53]
	v_mov_b32_e32 v52, v46
	v_mov_b32_e32 v53, v44
	v_mov_b32_e32 v44, v47
	v_mov_b32_e32 v46, v50
	v_mov_b32_e32 v47, v48
	v_pk_add_f32 v[44:45], v[52:53], v[44:45]
	v_mov_b32_e32 v48, v51
	v_pk_add_f32 v[44:45], v[44:45], v[46:47]
	s_nop 0
	v_pk_add_f32 v[44:45], v[44:45], v[48:49]
	ds_bpermute_b32 v47, v1, v45
	ds_bpermute_b32 v46, v1, v44
	s_waitcnt lgkmcnt(0)
	v_pk_add_f32 v[44:45], v[44:45], v[46:47]
	ds_bpermute_b32 v47, v3, v45
	ds_bpermute_b32 v46, v3, v44
	s_waitcnt lgkmcnt(0)
	v_pk_add_f32 v[44:45], v[44:45], v[46:47]
	ds_bpermute_b32 v47, v4, v45
	ds_bpermute_b32 v46, v4, v44
	s_waitcnt lgkmcnt(0)
	v_pk_add_f32 v[44:45], v[44:45], v[46:47]
	ds_bpermute_b32 v47, v5, v45
	ds_bpermute_b32 v46, v5, v44
	s_waitcnt lgkmcnt(0)
	v_pk_add_f32 v[44:45], v[44:45], v[46:47]
	ds_bpermute_b32 v47, v6, v45
	ds_bpermute_b32 v46, v6, v44
	s_waitcnt lgkmcnt(0)
	v_pk_add_f32 v[44:45], v[44:45], v[46:47]
	ds_bpermute_b32 v47, v7, v45
	ds_bpermute_b32 v46, v7, v44
	s_waitcnt lgkmcnt(0)
	v_pk_add_f32 v[44:45], v[44:45], v[46:47]
	s_nop 0
	v_pk_fma_f32 v[44:45], v[44:45], s[14:15], v[2:3] op_sel_hi:[1,0,0]
	s_nop 0
	v_mul_f32_e32 v46, 0x4b800000, v45
	v_cmp_gt_f32_e64 s[0:1], s15, v45
	v_mul_f32_e32 v47, 0x4b800000, v44
	v_cmp_gt_f32_e32 vcc, s15, v44
	v_cndmask_b32_e64 v45, v45, v46, s[0:1]
	v_rsq_f32_e32 v45, v45
	v_cndmask_b32_e32 v44, v44, v47, vcc
	v_rsq_f32_e32 v46, v44
	v_mul_f32_e32 v44, 0x45800000, v45
	v_cndmask_b32_e64 v44, v45, v44, s[0:1]
	v_mul_f32_e32 v47, 0x45800000, v46
	v_cndmask_b32_e32 v46, v46, v47, vcc
	v_pk_mul_f32 v[8:9], v[8:9], v[44:45] op_sel_hi:[1,0]
	v_pk_mul_f32 v[10:11], v[10:11], v[44:45] op_sel_hi:[1,0]
	v_pk_mul_f32 v[16:17], v[16:17], v[46:47] op_sel_hi:[1,0]
	v_pk_mul_f32 v[18:19], v[18:19], v[46:47] op_sel_hi:[1,0]
	v_pk_mul_f32 v[12:13], v[12:13], v[44:45] op_sel_hi:[1,0]
	v_pk_mul_f32 v[14:15], v[14:15], v[44:45] op_sel_hi:[1,0]
	v_pk_mul_f32 v[20:21], v[20:21], v[46:47] op_sel_hi:[1,0]
	v_pk_mul_f32 v[22:23], v[22:23], v[46:47] op_sel_hi:[1,0]
	v_pk_mul_f32 v[24:25], v[24:25], v[44:45] op_sel_hi:[1,0]
	v_pk_mul_f32 v[26:27], v[26:27], v[44:45] op_sel_hi:[1,0]
	v_pk_mul_f32 v[32:33], v[32:33], v[46:47] op_sel_hi:[1,0]
	v_pk_mul_f32 v[34:35], v[34:35], v[46:47] op_sel_hi:[1,0]
	v_pk_mul_f32 v[28:29], v[28:29], v[44:45] op_sel_hi:[1,0]
	v_pk_mul_f32 v[30:31], v[30:31], v[44:45] op_sel_hi:[1,0]
	v_pk_mul_f32 v[36:37], v[36:37], v[46:47] op_sel_hi:[1,0]
	v_pk_mul_f32 v[38:39], v[38:39], v[46:47] op_sel_hi:[1,0]
	v_cvt_pk_bf16_f32 v8, v8, v9
	v_cvt_pk_bf16_f32 v9, v10, v11
	v_cvt_pk_bf16_f32 v10, v16, v17
	v_cvt_pk_bf16_f32 v11, v18, v19
	v_cvt_pk_bf16_f32 v12, v12, v13
	v_cvt_pk_bf16_f32 v13, v14, v15
	v_cvt_pk_bf16_f32 v14, v20, v21
	v_cvt_pk_bf16_f32 v15, v22, v23
	v_cvt_pk_bf16_f32 v16, v24, v25
	v_cvt_pk_bf16_f32 v17, v26, v27
	v_cvt_pk_bf16_f32 v18, v32, v33
	v_cvt_pk_bf16_f32 v19, v34, v35
	v_cvt_pk_bf16_f32 v20, v28, v29
	v_cvt_pk_bf16_f32 v21, v30, v31
	v_cvt_pk_bf16_f32 v22, v36, v37
	v_cvt_pk_bf16_f32 v23, v38, v39
	global_store_dwordx2 v[40:41], v[8:9], off
	global_store_dwordx2 v[42:43], v[10:11], off
	global_store_dwordx2 v[40:41], v[12:13], off offset:512
	global_store_dwordx2 v[42:43], v[14:15], off offset:512
	global_store_dwordx2 v[40:41], v[16:17], off offset:1024
	global_store_dwordx2 v[42:43], v[18:19], off offset:1024
	global_store_dwordx2 v[40:41], v[20:21], off offset:1536
	global_store_dwordx2 v[42:43], v[22:23], off offset:1536
	s_waitcnt vmcnt(15)
	v_mov_b32_e32 v114, v77
	s_waitcnt vmcnt(14)
	v_mov_b32_e32 v115, v81
	s_waitcnt vmcnt(13)
	v_mov_b32_e32 v122, v85
	s_waitcnt vmcnt(12)
	v_mov_b32_e32 v123, v89
	v_mov_b32_e32 v112, v76
	v_mov_b32_e32 v113, v80
	v_mov_b32_e32 v120, v84
	v_mov_b32_e32 v121, v88
	s_waitcnt vmcnt(11)
	v_mov_b32_e32 v130, v93
	s_waitcnt vmcnt(10)
	v_mov_b32_e32 v131, v97
	s_waitcnt vmcnt(9)
	v_mov_b32_e32 v136, v101
	s_waitcnt vmcnt(8)
	v_mov_b32_e32 v137, v105
	v_pk_mul_f32 v[114:115], v[114:115], v[114:115]
	v_pk_mul_f32 v[122:123], v[122:123], v[122:123]
	v_mov_b32_e32 v116, v78
	v_mov_b32_e32 v117, v82
	v_mov_b32_e32 v124, v86
	v_mov_b32_e32 v125, v90
	v_mov_b32_e32 v128, v92
	v_mov_b32_e32 v129, v96
	v_mov_b32_e32 v134, v100
	v_mov_b32_e32 v135, v104
	v_pk_mul_f32 v[130:131], v[130:131], v[130:131]
	v_pk_mul_f32 v[136:137], v[136:137], v[136:137]
	v_pk_fma_f32 v[112:113], v[112:113], v[112:113], v[114:115]
	v_pk_fma_f32 v[114:115], v[120:121], v[120:121], v[122:123]
	v_mov_b32_e32 v118, v79
	v_mov_b32_e32 v119, v83
	v_mov_b32_e32 v126, v87
	v_mov_b32_e32 v127, v91
	v_mov_b32_e32 v132, v94
	v_mov_b32_e32 v133, v98
	v_mov_b32_e32 v140, v102
	v_mov_b32_e32 v141, v106
	v_pk_fma_f32 v[120:121], v[128:129], v[128:129], v[130:131]
	v_pk_fma_f32 v[122:123], v[134:135], v[134:135], v[136:137]
	v_pk_fma_f32 v[112:113], v[116:117], v[116:117], v[112:113]
	v_pk_fma_f32 v[114:115], v[124:125], v[124:125], v[114:115]
	v_mov_b32_e32 v138, v95
	v_mov_b32_e32 v139, v99
	v_mov_b32_e32 v142, v103
	v_mov_b32_e32 v143, v107
	v_pk_fma_f32 v[116:117], v[132:133], v[132:133], v[120:121]
	v_pk_fma_f32 v[120:121], v[140:141], v[140:141], v[122:123]
	v_pk_fma_f32 v[112:113], v[118:119], v[118:119], v[112:113]
	v_pk_fma_f32 v[114:115], v[126:127], v[126:127], v[114:115]
	v_pk_fma_f32 v[116:117], v[138:139], v[138:139], v[116:117]
	v_pk_fma_f32 v[118:119], v[142:143], v[142:143], v[120:121]
	v_mov_b32_e32 v120, v114
	v_mov_b32_e32 v121, v112
	v_mov_b32_e32 v112, v115
	v_mov_b32_e32 v114, v118
	v_mov_b32_e32 v115, v116
	v_pk_add_f32 v[112:113], v[120:121], v[112:113]
	v_mov_b32_e32 v116, v119
	v_pk_add_f32 v[112:113], v[112:113], v[114:115]
	s_nop 0
	v_pk_add_f32 v[112:113], v[112:113], v[116:117]
	ds_bpermute_b32 v115, v1, v113
	ds_bpermute_b32 v114, v1, v112
	s_waitcnt lgkmcnt(0)
	v_pk_add_f32 v[112:113], v[112:113], v[114:115]
	ds_bpermute_b32 v115, v3, v113
	ds_bpermute_b32 v114, v3, v112
	s_waitcnt lgkmcnt(0)
	v_pk_add_f32 v[112:113], v[112:113], v[114:115]
	ds_bpermute_b32 v115, v4, v113
	ds_bpermute_b32 v114, v4, v112
	s_waitcnt lgkmcnt(0)
	v_pk_add_f32 v[112:113], v[112:113], v[114:115]
	ds_bpermute_b32 v115, v5, v113
	ds_bpermute_b32 v114, v5, v112
	s_waitcnt lgkmcnt(0)
	v_pk_add_f32 v[112:113], v[112:113], v[114:115]
	ds_bpermute_b32 v115, v6, v113
	ds_bpermute_b32 v114, v6, v112
	s_waitcnt lgkmcnt(0)
	v_pk_add_f32 v[112:113], v[112:113], v[114:115]
	ds_bpermute_b32 v115, v7, v113
	ds_bpermute_b32 v114, v7, v112
	s_waitcnt lgkmcnt(0)
	v_pk_add_f32 v[112:113], v[112:113], v[114:115]
	s_nop 0
	v_pk_fma_f32 v[112:113], v[112:113], s[14:15], v[2:3] op_sel_hi:[1,0,0]
	s_nop 0
	v_mul_f32_e32 v114, 0x4b800000, v113
	v_cmp_gt_f32_e64 s[0:1], s15, v113
	v_mul_f32_e32 v115, 0x4b800000, v112
	v_cmp_gt_f32_e32 vcc, s15, v112
	v_cndmask_b32_e64 v113, v113, v114, s[0:1]
	v_rsq_f32_e32 v113, v113
	v_cndmask_b32_e32 v112, v112, v115, vcc
	v_rsq_f32_e32 v114, v112
	v_mul_f32_e32 v112, 0x45800000, v113
	v_cndmask_b32_e64 v112, v113, v112, s[0:1]
	v_mul_f32_e32 v115, 0x45800000, v114
	v_cndmask_b32_e32 v114, v114, v115, vcc
	v_pk_mul_f32 v[76:77], v[76:77], v[112:113] op_sel_hi:[1,0]
	v_pk_mul_f32 v[78:79], v[78:79], v[112:113] op_sel_hi:[1,0]
	v_pk_mul_f32 v[84:85], v[84:85], v[114:115] op_sel_hi:[1,0]
	v_pk_mul_f32 v[86:87], v[86:87], v[114:115] op_sel_hi:[1,0]
	v_pk_mul_f32 v[80:81], v[80:81], v[112:113] op_sel_hi:[1,0]
	v_pk_mul_f32 v[82:83], v[82:83], v[112:113] op_sel_hi:[1,0]
	v_pk_mul_f32 v[88:89], v[88:89], v[114:115] op_sel_hi:[1,0]
	v_pk_mul_f32 v[90:91], v[90:91], v[114:115] op_sel_hi:[1,0]
	v_pk_mul_f32 v[92:93], v[92:93], v[112:113] op_sel_hi:[1,0]
	v_pk_mul_f32 v[94:95], v[94:95], v[112:113] op_sel_hi:[1,0]
	v_pk_mul_f32 v[100:101], v[100:101], v[114:115] op_sel_hi:[1,0]
	v_pk_mul_f32 v[102:103], v[102:103], v[114:115] op_sel_hi:[1,0]
	v_pk_mul_f32 v[96:97], v[96:97], v[112:113] op_sel_hi:[1,0]
	v_pk_mul_f32 v[98:99], v[98:99], v[112:113] op_sel_hi:[1,0]
	v_pk_mul_f32 v[104:105], v[104:105], v[114:115] op_sel_hi:[1,0]
	v_pk_mul_f32 v[106:107], v[106:107], v[114:115] op_sel_hi:[1,0]
	v_cvt_pk_bf16_f32 v76, v76, v77
	v_cvt_pk_bf16_f32 v77, v78, v79
	v_cvt_pk_bf16_f32 v78, v84, v85
	v_cvt_pk_bf16_f32 v79, v86, v87
	v_cvt_pk_bf16_f32 v80, v80, v81
	v_cvt_pk_bf16_f32 v81, v82, v83
	v_cvt_pk_bf16_f32 v82, v88, v89
	v_cvt_pk_bf16_f32 v83, v90, v91
	v_cvt_pk_bf16_f32 v84, v92, v93
	v_cvt_pk_bf16_f32 v85, v94, v95
	v_cvt_pk_bf16_f32 v86, v100, v101
	v_cvt_pk_bf16_f32 v87, v102, v103
	v_cvt_pk_bf16_f32 v88, v96, v97
	v_cvt_pk_bf16_f32 v89, v98, v99
	v_cvt_pk_bf16_f32 v90, v104, v105
	v_cvt_pk_bf16_f32 v91, v106, v107
	global_store_dwordx2 v[108:109], v[76:77], off
	global_store_dwordx2 v[110:111], v[78:79], off
	global_store_dwordx2 v[108:109], v[80:81], off offset:512
	global_store_dwordx2 v[110:111], v[82:83], off offset:512
	global_store_dwordx2 v[108:109], v[84:85], off offset:1024
	global_store_dwordx2 v[110:111], v[86:87], off offset:1024
	global_store_dwordx2 v[108:109], v[88:89], off offset:1536
	global_store_dwordx2 v[110:111], v[90:91], off offset:1536
	s_cbranch_scc1 .LBB0_111

.LBB0_189:
	v_lshl_add_u64 v[28:29], s[8:9], 0, v[148:149]
	v_lshl_add_u64 v[36:37], s[10:11], 0, v[148:149]
	global_load_dwordx4 v[8:11], v[28:29], off
	global_load_dwordx4 v[12:15], v[28:29], off offset:1024
	global_load_dwordx4 v[16:19], v[36:37], off
	global_load_dwordx4 v[20:23], v[36:37], off offset:1024
	global_load_dwordx4 v[24:27], v[28:29], off offset:2048
	s_nop 0
	global_load_dwordx4 v[28:31], v[28:29], off offset:3072
	s_nop 0
	global_load_dwordx4 v[32:35], v[36:37], off offset:2048
	s_nop 0
	global_load_dwordx4 v[36:39], v[36:37], off offset:3072
	s_add_i32 s3, s3, 16
	v_lshl_add_u64 v[42:43], s[6:7], 0, v[146:147]
	s_add_u32 s6, s6, 0x8000
	s_addc_u32 s7, s7, 0
	s_add_u32 s8, s8, 0x10000
	s_addc_u32 s9, s9, 0
	s_add_u32 s10, s10, 0x10000
	s_addc_u32 s11, s11, 0
	v_lshl_add_u64 v[40:41], s[14:15], 0, v[146:147]
	s_add_u32 s14, s14, 0x8000
	s_addc_u32 s15, s15, 0
	s_cmp_lt_i32 s3, s2
	v_lshl_add_u64 v[96:97], s[8:9], 0, v[148:149]
	v_lshl_add_u64 v[104:105], s[10:11], 0, v[148:149]
	global_load_dwordx4 v[76:79], v[96:97], off
	global_load_dwordx4 v[80:83], v[96:97], off offset:1024
	global_load_dwordx4 v[84:87], v[104:105], off
	global_load_dwordx4 v[88:91], v[104:105], off offset:1024
	global_load_dwordx4 v[92:95], v[96:97], off offset:2048
	s_nop 0
	global_load_dwordx4 v[96:99], v[96:97], off offset:3072
	s_nop 0
	global_load_dwordx4 v[100:103], v[104:105], off offset:2048
	s_nop 0
	global_load_dwordx4 v[104:107], v[104:105], off offset:3072
	s_add_i32 s3, s3, 16
	v_lshl_add_u64 v[110:111], s[6:7], 0, v[146:147]
	s_add_u32 s6, s6, 0x8000
	s_addc_u32 s7, s7, 0
	s_add_u32 s8, s8, 0x10000
	s_addc_u32 s9, s9, 0
	s_add_u32 s10, s10, 0x10000
	s_addc_u32 s11, s11, 0
	v_lshl_add_u64 v[108:109], s[14:15], 0, v[146:147]
	s_add_u32 s14, s14, 0x8000
	s_addc_u32 s15, s15, 0
	s_cmp_lt_i32 s3, s2
	s_waitcnt vmcnt(8)
	v_mov_b32_e32 v46, v9
	v_mov_b32_e32 v47, v13
	v_mov_b32_e32 v54, v17
	v_mov_b32_e32 v55, v21
	v_mov_b32_e32 v44, v8
	v_mov_b32_e32 v45, v12
	v_mov_b32_e32 v52, v16
	v_mov_b32_e32 v53, v20
	v_mov_b32_e32 v62, v25
	v_mov_b32_e32 v63, v29
	v_mov_b32_e32 v70, v33
	v_mov_b32_e32 v71, v37
	v_pk_mul_f32 v[46:47], v[46:47], v[46:47]
	v_pk_mul_f32 v[54:55], v[54:55], v[54:55]
	v_mov_b32_e32 v48, v10
	v_mov_b32_e32 v49, v14
	v_mov_b32_e32 v56, v18
	v_mov_b32_e32 v57, v22
	v_mov_b32_e32 v60, v24
	v_mov_b32_e32 v61, v28
	v_mov_b32_e32 v68, v32
	v_mov_b32_e32 v69, v36
	v_pk_mul_f32 v[62:63], v[62:63], v[62:63]
	v_pk_mul_f32 v[70:71], v[70:71], v[70:71]
	v_pk_fma_f32 v[44:45], v[44:45], v[44:45], v[46:47]
	v_pk_fma_f32 v[46:47], v[52:53], v[52:53], v[54:55]
	v_mov_b32_e32 v50, v11
	v_mov_b32_e32 v51, v15
	v_mov_b32_e32 v58, v19
	v_mov_b32_e32 v59, v23
	v_mov_b32_e32 v64, v26
	v_mov_b32_e32 v65, v30
	v_mov_b32_e32 v72, v34
	v_mov_b32_e32 v73, v38
	v_pk_fma_f32 v[52:53], v[60:61], v[60:61], v[62:63]
	v_pk_fma_f32 v[54:55], v[68:69], v[68:69], v[70:71]
	v_pk_fma_f32 v[44:45], v[48:49], v[48:49], v[44:45]
	v_pk_fma_f32 v[46:47], v[56:57], v[56:57], v[46:47]
	v_mov_b32_e32 v66, v27
	v_mov_b32_e32 v67, v31
	v_mov_b32_e32 v74, v35
	v_mov_b32_e32 v75, v39
	v_pk_fma_f32 v[48:49], v[64:65], v[64:65], v[52:53]
	v_pk_fma_f32 v[52:53], v[72:73], v[72:73], v[54:55]
	v_pk_fma_f32 v[44:45], v[50:51], v[50:51], v[44:45]
	v_pk_fma_f32 v[46:47], v[58:59], v[58:59], v[46:47]
	v_pk_fma_f32 v[48:49], v[66:67], v[66:67], v[48:49]
	v_pk_fma_f32 v[50:51], v[74:75], v[74:75], v[52:53]
	v_mov_b32_e32 v52, v46
	v_mov_b32_e32 v53, v44
	v_mov_b32_e32 v44, v47
	v_mov_b32_e32 v46, v50
	v_mov_b32_e32 v47, v48
	v_pk_add_f32 v[44:45], v[52:53], v[44:45]
	v_mov_b32_e32 v48, v51
	v_pk_add_f32 v[44:45], v[44:45], v[46:47]
	s_nop 0
	v_pk_add_f32 v[44:45], v[44:45], v[48:49]
	ds_bpermute_b32 v47, v1, v45
	ds_bpermute_b32 v46, v1, v44
	s_waitcnt lgkmcnt(0)
	v_pk_add_f32 v[44:45], v[44:45], v[46:47]
	ds_bpermute_b32 v47, v3, v45
	ds_bpermute_b32 v46, v3, v44
	s_waitcnt lgkmcnt(0)
	v_pk_add_f32 v[44:45], v[44:45], v[46:47]
	ds_bpermute_b32 v47, v4, v45
	ds_bpermute_b32 v46, v4, v44
	s_waitcnt lgkmcnt(0)
	v_pk_add_f32 v[44:45], v[44:45], v[46:47]
	ds_bpermute_b32 v47, v5, v45
	ds_bpermute_b32 v46, v5, v44
	s_waitcnt lgkmcnt(0)
	v_pk_add_f32 v[44:45], v[44:45], v[46:47]
	ds_bpermute_b32 v47, v6, v45
	ds_bpermute_b32 v46, v6, v44
	s_waitcnt lgkmcnt(0)
	v_pk_add_f32 v[44:45], v[44:45], v[46:47]
	ds_bpermute_b32 v47, v7, v45
	ds_bpermute_b32 v46, v7, v44
	s_waitcnt lgkmcnt(0)
	v_pk_add_f32 v[44:45], v[44:45], v[46:47]
	s_nop 0
	v_pk_fma_f32 v[44:45], v[44:45], s[18:19], v[2:3] op_sel_hi:[1,0,0]
	s_nop 0
	v_mul_f32_e32 v46, 0x4b800000, v45
	v_cmp_gt_f32_e64 s[0:1], s4, v45
	v_mul_f32_e32 v47, 0x4b800000, v44
	v_cmp_gt_f32_e32 vcc, s4, v44
	v_cndmask_b32_e64 v45, v45, v46, s[0:1]
	v_rsq_f32_e32 v45, v45
	v_cndmask_b32_e32 v44, v44, v47, vcc
	v_rsq_f32_e32 v46, v44
	v_mul_f32_e32 v44, 0x45800000, v45
	v_cndmask_b32_e64 v44, v45, v44, s[0:1]
	v_mul_f32_e32 v47, 0x45800000, v46
	v_cndmask_b32_e32 v46, v46, v47, vcc
	v_pk_mul_f32 v[8:9], v[8:9], v[44:45] op_sel_hi:[1,0]
	v_pk_mul_f32 v[10:11], v[10:11], v[44:45] op_sel_hi:[1,0]
	v_pk_mul_f32 v[16:17], v[16:17], v[46:47] op_sel_hi:[1,0]
	v_pk_mul_f32 v[18:19], v[18:19], v[46:47] op_sel_hi:[1,0]
	v_pk_mul_f32 v[12:13], v[12:13], v[44:45] op_sel_hi:[1,0]
	v_pk_mul_f32 v[14:15], v[14:15], v[44:45] op_sel_hi:[1,0]
	v_pk_mul_f32 v[20:21], v[20:21], v[46:47] op_sel_hi:[1,0]
	v_pk_mul_f32 v[22:23], v[22:23], v[46:47] op_sel_hi:[1,0]
	v_pk_mul_f32 v[24:25], v[24:25], v[44:45] op_sel_hi:[1,0]
	v_pk_mul_f32 v[26:27], v[26:27], v[44:45] op_sel_hi:[1,0]
	v_pk_mul_f32 v[32:33], v[32:33], v[46:47] op_sel_hi:[1,0]
	v_pk_mul_f32 v[34:35], v[34:35], v[46:47] op_sel_hi:[1,0]
	v_pk_mul_f32 v[28:29], v[28:29], v[44:45] op_sel_hi:[1,0]
	v_pk_mul_f32 v[30:31], v[30:31], v[44:45] op_sel_hi:[1,0]
	v_pk_mul_f32 v[36:37], v[36:37], v[46:47] op_sel_hi:[1,0]
	v_pk_mul_f32 v[38:39], v[38:39], v[46:47] op_sel_hi:[1,0]
	v_cvt_pk_bf16_f32 v8, v8, v9
	v_cvt_pk_bf16_f32 v9, v10, v11
	v_cvt_pk_bf16_f32 v10, v16, v17
	v_cvt_pk_bf16_f32 v11, v18, v19
	v_cvt_pk_bf16_f32 v12, v12, v13
	v_cvt_pk_bf16_f32 v13, v14, v15
	v_cvt_pk_bf16_f32 v14, v20, v21
	v_cvt_pk_bf16_f32 v15, v22, v23
	v_cvt_pk_bf16_f32 v16, v24, v25
	v_cvt_pk_bf16_f32 v17, v26, v27
	v_cvt_pk_bf16_f32 v18, v32, v33
	v_cvt_pk_bf16_f32 v19, v34, v35
	v_cvt_pk_bf16_f32 v20, v28, v29
	v_cvt_pk_bf16_f32 v21, v30, v31
	v_cvt_pk_bf16_f32 v22, v36, v37
	v_cvt_pk_bf16_f32 v23, v38, v39
	global_store_dwordx2 v[40:41], v[8:9], off
	global_store_dwordx2 v[42:43], v[10:11], off
	global_store_dwordx2 v[40:41], v[12:13], off offset:512
	global_store_dwordx2 v[42:43], v[14:15], off offset:512
	global_store_dwordx2 v[40:41], v[16:17], off offset:1024
	global_store_dwordx2 v[42:43], v[18:19], off offset:1024
	global_store_dwordx2 v[40:41], v[20:21], off offset:1536
	global_store_dwordx2 v[42:43], v[22:23], off offset:1536
	s_waitcnt vmcnt(8)
	v_mov_b32_e32 v114, v77
	v_mov_b32_e32 v115, v81
	v_mov_b32_e32 v122, v85
	v_mov_b32_e32 v123, v89
	v_mov_b32_e32 v112, v76
	v_mov_b32_e32 v113, v80
	v_mov_b32_e32 v120, v84
	v_mov_b32_e32 v121, v88
	v_mov_b32_e32 v130, v93
	v_mov_b32_e32 v131, v97
	v_mov_b32_e32 v138, v101
	v_mov_b32_e32 v139, v105
	v_pk_mul_f32 v[114:115], v[114:115], v[114:115]
	v_pk_mul_f32 v[122:123], v[122:123], v[122:123]
	v_mov_b32_e32 v116, v78
	v_mov_b32_e32 v117, v82
	v_mov_b32_e32 v124, v86
	v_mov_b32_e32 v125, v90
	v_mov_b32_e32 v128, v92
	v_mov_b32_e32 v129, v96
	v_mov_b32_e32 v136, v100
	v_mov_b32_e32 v137, v104
	v_pk_mul_f32 v[130:131], v[130:131], v[130:131]
	v_pk_mul_f32 v[138:139], v[138:139], v[138:139]
	v_pk_fma_f32 v[112:113], v[112:113], v[112:113], v[114:115]
	v_pk_fma_f32 v[114:115], v[120:121], v[120:121], v[122:123]
	v_mov_b32_e32 v118, v79
	v_mov_b32_e32 v119, v83
	v_mov_b32_e32 v126, v87
	v_mov_b32_e32 v127, v91
	v_mov_b32_e32 v132, v94
	v_mov_b32_e32 v133, v98
	v_mov_b32_e32 v140, v102
	v_mov_b32_e32 v141, v106
	v_pk_fma_f32 v[120:121], v[128:129], v[128:129], v[130:131]
	v_pk_fma_f32 v[122:123], v[136:137], v[136:137], v[138:139]
	v_pk_fma_f32 v[112:113], v[116:117], v[116:117], v[112:113]
	v_pk_fma_f32 v[114:115], v[124:125], v[124:125], v[114:115]
	v_mov_b32_e32 v134, v95
	v_mov_b32_e32 v135, v99
	v_mov_b32_e32 v142, v103
	v_mov_b32_e32 v143, v107
	v_pk_fma_f32 v[116:117], v[132:133], v[132:133], v[120:121]
	v_pk_fma_f32 v[120:121], v[140:141], v[140:141], v[122:123]
	v_pk_fma_f32 v[112:113], v[118:119], v[118:119], v[112:113]
	v_pk_fma_f32 v[114:115], v[126:127], v[126:127], v[114:115]
	v_pk_fma_f32 v[116:117], v[134:135], v[134:135], v[116:117]
	v_pk_fma_f32 v[118:119], v[142:143], v[142:143], v[120:121]
	v_mov_b32_e32 v120, v114
	v_mov_b32_e32 v121, v112
	v_mov_b32_e32 v112, v115
	v_mov_b32_e32 v114, v118
	v_mov_b32_e32 v115, v116
	v_pk_add_f32 v[112:113], v[120:121], v[112:113]
	v_mov_b32_e32 v116, v119
	v_pk_add_f32 v[112:113], v[112:113], v[114:115]
	s_nop 0
	v_pk_add_f32 v[112:113], v[112:113], v[116:117]
	ds_bpermute_b32 v115, v1, v113
	ds_bpermute_b32 v114, v1, v112
	s_waitcnt lgkmcnt(0)
	v_pk_add_f32 v[112:113], v[112:113], v[114:115]
	ds_bpermute_b32 v115, v3, v113
	ds_bpermute_b32 v114, v3, v112
	s_waitcnt lgkmcnt(0)
	v_pk_add_f32 v[112:113], v[112:113], v[114:115]
	ds_bpermute_b32 v115, v4, v113
	ds_bpermute_b32 v114, v4, v112
	s_waitcnt lgkmcnt(0)
	v_pk_add_f32 v[112:113], v[112:113], v[114:115]
	ds_bpermute_b32 v115, v5, v113
	ds_bpermute_b32 v114, v5, v112
	s_waitcnt lgkmcnt(0)
	v_pk_add_f32 v[112:113], v[112:113], v[114:115]
	ds_bpermute_b32 v115, v6, v113
	ds_bpermute_b32 v114, v6, v112
	s_waitcnt lgkmcnt(0)
	v_pk_add_f32 v[112:113], v[112:113], v[114:115]
	ds_bpermute_b32 v115, v7, v113
	ds_bpermute_b32 v114, v7, v112
	s_waitcnt lgkmcnt(0)
	v_pk_add_f32 v[112:113], v[112:113], v[114:115]
	s_nop 0
	v_pk_fma_f32 v[112:113], v[112:113], s[18:19], v[2:3] op_sel_hi:[1,0,0]
	s_nop 0
	v_mul_f32_e32 v114, 0x4b800000, v113
	v_cmp_gt_f32_e64 s[0:1], s4, v113
	v_mul_f32_e32 v115, 0x4b800000, v112
	v_cmp_gt_f32_e32 vcc, s4, v112
	v_cndmask_b32_e64 v113, v113, v114, s[0:1]
	v_rsq_f32_e32 v113, v113
	v_cndmask_b32_e32 v112, v112, v115, vcc
	v_rsq_f32_e32 v114, v112
	v_mul_f32_e32 v112, 0x45800000, v113
	v_cndmask_b32_e64 v112, v113, v112, s[0:1]
	v_mul_f32_e32 v115, 0x45800000, v114
	v_cndmask_b32_e32 v114, v114, v115, vcc
	v_pk_mul_f32 v[76:77], v[76:77], v[112:113] op_sel_hi:[1,0]
	v_pk_mul_f32 v[78:79], v[78:79], v[112:113] op_sel_hi:[1,0]
	v_pk_mul_f32 v[84:85], v[84:85], v[114:115] op_sel_hi:[1,0]
	v_pk_mul_f32 v[86:87], v[86:87], v[114:115] op_sel_hi:[1,0]
	v_pk_mul_f32 v[80:81], v[80:81], v[112:113] op_sel_hi:[1,0]
	v_pk_mul_f32 v[82:83], v[82:83], v[112:113] op_sel_hi:[1,0]
	v_pk_mul_f32 v[88:89], v[88:89], v[114:115] op_sel_hi:[1,0]
	v_pk_mul_f32 v[90:91], v[90:91], v[114:115] op_sel_hi:[1,0]
	v_pk_mul_f32 v[92:93], v[92:93], v[112:113] op_sel_hi:[1,0]
	v_pk_mul_f32 v[94:95], v[94:95], v[112:113] op_sel_hi:[1,0]
	v_pk_mul_f32 v[100:101], v[100:101], v[114:115] op_sel_hi:[1,0]
	v_pk_mul_f32 v[102:103], v[102:103], v[114:115] op_sel_hi:[1,0]
	v_pk_mul_f32 v[96:97], v[96:97], v[112:113] op_sel_hi:[1,0]
	v_pk_mul_f32 v[98:99], v[98:99], v[112:113] op_sel_hi:[1,0]
	v_pk_mul_f32 v[104:105], v[104:105], v[114:115] op_sel_hi:[1,0]
	v_pk_mul_f32 v[106:107], v[106:107], v[114:115] op_sel_hi:[1,0]
	v_cvt_pk_bf16_f32 v76, v76, v77
	v_cvt_pk_bf16_f32 v77, v78, v79
	v_cvt_pk_bf16_f32 v78, v84, v85
	v_cvt_pk_bf16_f32 v79, v86, v87
	v_cvt_pk_bf16_f32 v80, v80, v81
	v_cvt_pk_bf16_f32 v81, v82, v83
	v_cvt_pk_bf16_f32 v82, v88, v89
	v_cvt_pk_bf16_f32 v83, v90, v91
	v_cvt_pk_bf16_f32 v84, v92, v93
	v_cvt_pk_bf16_f32 v85, v94, v95
	v_cvt_pk_bf16_f32 v86, v100, v101
	v_cvt_pk_bf16_f32 v87, v102, v103
	v_cvt_pk_bf16_f32 v88, v96, v97
	v_cvt_pk_bf16_f32 v89, v98, v99
	v_cvt_pk_bf16_f32 v90, v104, v105
	v_cvt_pk_bf16_f32 v91, v106, v107
	global_store_dwordx2 v[108:109], v[76:77], off
	global_store_dwordx2 v[110:111], v[78:79], off
	global_store_dwordx2 v[108:109], v[80:81], off offset:512
	global_store_dwordx2 v[110:111], v[82:83], off offset:512
	global_store_dwordx2 v[108:109], v[84:85], off offset:1024
	global_store_dwordx2 v[110:111], v[86:87], off offset:1024
	global_store_dwordx2 v[108:109], v[88:89], off offset:1536
	global_store_dwordx2 v[110:111], v[90:91], off offset:1536
	s_cbranch_scc1 .LBB0_189
